# chip-wide barriers 1-3: early L2 write-back issued by wave 1 of every arriving workgroup; + XCD-local seams (3us stagger) + P4/P6' epilogue rewrites (wide d_out stores)
# baseline (speedup 1.0000x reference)
.LBB0_58:
	s_or_b64 exec, exec, s[0:1]
	v_mbcnt_lo_u32_b32 v0, -1, 0
	v_mbcnt_hi_u32_b32 v0, -1, v0
	s_waitcnt vmcnt(0)
	s_and_b32 s0, s26, 0xffffffc0
	v_sub_u32_e32 v0, 0, v0
	v_cmp_eq_u32_e32 vcc, s0, v0
	s_barrier
	s_cmp_eq_u32 s0, 64
	s_cbranch_scc0 .Lewb_b1
	buffer_wbl2 sc1
.Lewb_b1:
	v_writelane_b32 v254, s0, 6
	s_and_saveexec_b64 s[0:1], vcc
	v_writelane_b32 v254, s64, 7
	s_nop 1
	v_writelane_b32 v254, s65, 8
	v_writelane_b32 v254, s66, 9
	v_writelane_b32 v254, s67, 10
	v_writelane_b32 v254, s42, 11
	v_writelane_b32 v254, s43, 12
	s_cbranch_execz .LBB0_110
	s_add_i32 s4, 0, 0x20400
	v_mov_b32_e32 v0, s4
	s_waitcnt vmcnt(0) expcnt(0) lgkmcnt(0)
	ds_read_b32 v2, v0
	s_add_i32 s4, 0, 0x20404
	v_mov_b32_e32 v0, s4
	ds_read_b32 v0, v0
	s_waitcnt lgkmcnt(1)
	v_cmp_ne_u32_e32 vcc, 0, v2
	s_cbranch_vccnz .LBB0_74
	s_add_u32 s4, s66, 0x40200
	s_addc_u32 s5, s67, 0
	s_add_u32 s6, s66, 0x40400
	s_addc_u32 s7, s67, 0
	s_add_u32 s10, s66, 0x40500
	s_addc_u32 s11, s67, 0
	s_add_u32 s18, s66, 0x40600
	s_addc_u32 s19, s67, 0
	s_add_u32 s34, s66, 0x40700
	s_addc_u32 s35, s67, 0
	s_add_u32 s46, s66, 0x40800
	s_addc_u32 s47, s67, 0
	s_add_u32 s48, s66, 0x40900
	s_addc_u32 s49, s67, 0
	s_add_u32 s50, s66, 0x40a00
	s_addc_u32 s51, s67, 0
	s_add_u32 s52, s66, 0x40b00
	s_addc_u32 s53, s67, 0
	s_add_u32 s54, s66, 0x40c00
	s_addc_u32 s55, s67, 0
	s_add_u32 s56, s66, 0x40d00
	s_addc_u32 s57, s67, 0
	s_add_u32 s58, s66, 0x40e00
	s_addc_u32 s59, s67, 0
	s_add_u32 s60, s66, 0x40f00
	s_addc_u32 s61, s67, 0
	s_add_u32 s62, s66, 0x41000
	s_mov_b64 s[28:29], s[64:65]
	s_addc_u32 s63, s67, 0
	s_mov_b64 s[30:31], s[66:67]
	s_add_u32 s64, s30, 0x41100
	s_addc_u32 s65, s31, 0
	s_add_u32 s66, s30, 0x41200
	s_addc_u32 s67, s31, 0
	s_add_u32 s68, s30, 0x41300
	s_addc_u32 s69, s31, 0
	s_mov_b32 s20, 1
	v_mov_b32_e32 v16, 0
	s_branch .LBB0_62

.LBB0_217:
	s_waitcnt vmcnt(0)
	s_barrier
	v_mbcnt_lo_u32_b32 v0, -1, 0
	v_mbcnt_hi_u32_b32 v0, -1, v0
	s_waitcnt vmcnt(0)
	v_readlane_b32 s0, v254, 6
	v_sub_u32_e32 v0, 0, v0
	s_waitcnt vmcnt(0) lgkmcnt(0)
	v_cmp_eq_u32_e32 vcc, s0, v0
	s_barrier
	s_cmp_eq_u32 s0, 64
	s_cbranch_scc0 .Lewb_b2
	buffer_wbl2 sc1
.Lewb_b2:
	s_and_saveexec_b64 s[0:1], vcc
	v_readlane_b32 s64, v254, 7
	v_readlane_b32 s65, v254, 8
	v_readlane_b32 s66, v254, 9
	v_readlane_b32 s67, v254, 10
	s_cbranch_execz .LBB0_269
	s_add_i32 s4, 0, 0x20400
	v_mov_b32_e32 v0, s4
	s_waitcnt vmcnt(0) expcnt(0) lgkmcnt(0)
	ds_read_b32 v2, v0
	s_add_i32 s4, 0, 0x20404
	v_mov_b32_e32 v0, s4
	ds_read_b32 v0, v0
	s_waitcnt lgkmcnt(1)
	v_cmp_ne_u32_e32 vcc, 0, v2
	s_cbranch_vccnz .LBB0_233
	s_add_u32 s4, s66, 0x40200
	s_addc_u32 s5, s67, 0
	s_add_u32 s48, s66, 0x40400
	s_addc_u32 s49, s67, 0
	s_add_u32 s52, s66, 0x40500
	s_addc_u32 s53, s67, 0
	s_add_u32 s54, s66, 0x40600
	s_addc_u32 s55, s67, 0
	v_writelane_b32 v254, s80, 30
	s_add_u32 s56, s66, 0x40700
	s_addc_u32 s57, s67, 0
	v_writelane_b32 v254, s81, 31
	v_writelane_b32 v254, s82, 32
	s_add_u32 s58, s66, 0x40800
	v_writelane_b32 v254, s83, 33
	s_addc_u32 s59, s67, 0
	v_writelane_b32 v254, s84, 34
	s_add_u32 s60, s66, 0x40900
	v_writelane_b32 v254, s85, 35
	s_addc_u32 s61, s67, 0
	v_writelane_b32 v254, s86, 36
	s_add_u32 s62, s66, 0x40a00
	v_writelane_b32 v254, s87, 37
	s_addc_u32 s63, s67, 0
	s_mov_b64 s[82:83], s[66:67]
	s_mov_b64 s[80:81], s[64:65]
	s_add_u32 s64, s82, 0x40b00
	s_addc_u32 s65, s83, 0
	s_add_u32 s66, s82, 0x40c00
	s_addc_u32 s67, s83, 0
	s_add_u32 s68, s82, 0x40d00
	s_addc_u32 s69, s83, 0
	s_add_u32 s70, s82, 0x40e00
	s_addc_u32 s71, s83, 0
	s_add_u32 s72, s82, 0x40f00
	s_addc_u32 s73, s83, 0
	s_add_u32 s74, s82, 0x41000
	s_addc_u32 s75, s83, 0
	s_add_u32 s76, s82, 0x41100
	s_addc_u32 s77, s83, 0
	s_add_u32 s78, s82, 0x41200
	s_addc_u32 s79, s83, 0
	s_add_u32 s80, s82, 0x41300
	s_addc_u32 s81, s83, 0
	s_mov_b32 s21, 1
	v_mov_b32_e32 v16, 0
	s_branch .LBB0_221

.LBB0_340:
	v_mbcnt_lo_u32_b32 v0, -1, 0
	v_mbcnt_hi_u32_b32 v0, -1, v0
	s_waitcnt vmcnt(0)
	v_readlane_b32 s0, v254, 6
	v_sub_u32_e32 v0, 0, v0
	s_waitcnt vmcnt(0) lgkmcnt(0)
	v_cmp_eq_u32_e32 vcc, s0, v0
	s_barrier
	s_cmp_eq_u32 s0, 64
	s_cbranch_scc0 .Lewb_b3
	buffer_wbl2 sc1
.Lewb_b3:
	s_and_saveexec_b64 s[0:1], vcc
	v_readlane_b32 s84, v254, 18
	v_readlane_b32 s85, v254, 19
	s_cbranch_execz .LBB0_392
	s_add_i32 s4, 0, 0x20400
	v_mov_b32_e32 v0, s4
	s_waitcnt vmcnt(0) expcnt(0) lgkmcnt(0)
	ds_read_b32 v2, v0
	s_add_i32 s4, 0, 0x20404
	v_mov_b32_e32 v0, s4
	ds_read_b32 v0, v0
	s_waitcnt lgkmcnt(1)
	v_cmp_ne_u32_e32 vcc, 0, v2
	s_cbranch_vccnz .LBB0_356
	s_add_u32 s4, s66, 0x40200
	s_addc_u32 s5, s67, 0
	s_add_u32 s8, s66, 0x40400
	s_addc_u32 s9, s67, 0
	s_add_u32 s10, s66, 0x40500
	s_addc_u32 s11, s67, 0
	s_add_u32 s12, s66, 0x40600
	s_addc_u32 s13, s67, 0
	s_add_u32 s14, s66, 0x40700
	s_addc_u32 s15, s67, 0
	s_add_u32 s16, s66, 0x40800
	s_addc_u32 s17, s67, 0
	s_add_u32 s22, s66, 0x40900
	s_addc_u32 s23, s67, 0
	s_add_u32 s24, s66, 0x40a00
	s_addc_u32 s25, s67, 0
	s_add_u32 s42, s66, 0x40b00
	s_addc_u32 s43, s67, 0
	s_add_u32 s44, s66, 0x40c00
	s_addc_u32 s45, s67, 0
	s_add_u32 s46, s66, 0x40d00
	s_addc_u32 s47, s67, 0
	s_add_u32 s50, s66, 0x40e00
	s_addc_u32 s51, s67, 0
	s_add_u32 s52, s66, 0x40f00
	s_addc_u32 s53, s67, 0
	s_add_u32 s54, s66, 0x41000
	s_addc_u32 s55, s67, 0
	s_add_u32 s56, s66, 0x41100
	s_addc_u32 s57, s67, 0
	s_add_u32 s58, s66, 0x41200
	s_addc_u32 s59, s67, 0
	s_add_u32 s60, s66, 0x41300
	s_addc_u32 s61, s67, 0
	s_mov_b32 s20, 1
	v_mov_b32_e32 v16, 0
	s_branch .LBB0_344
